# k50: k49 + P1 row pairs split evenly over all 256 workgroups (129 pairs each) instead of ceil() per wave with the last 13 workgroups idle
# baseline (speedup 1.0000x reference)
; #define LAS __attribute__((address_space(3)))
; __global__ void __launch_bounds__(NTHR, 2) hymba_fwd(Params P) {
;     ...
;         __syncthreads();
;         LAS float* w8 = (LAS float*)lds;
; #pragma unroll
;         for (int i0 = 0; i0 < 8192; i0 += NTHR) { const int i = i0 + tid, c = i >> 10, k = i & 1023; w8[i] = P.w_in[(size_t)k * INW + NPROJ + c]; }
;         __syncthreads();
;         const int gw = blk * NWAVES + wave, NGW = G * NWAVES;
;         constexpr int NPAIR = MT / 2; const int per = (NPAIR + NGW - 1) / NGW;
;         const int p_lo = gw * per, p_hi = (p_lo + per < NPAIR) ? p_lo + per : NPAIR;
.LBB0_140:
	s_or_b64 exec, exec, s[0:1]
	v_mov_b32_e32 v2, v208
	s_waitcnt lgkmcnt(0)
	s_barrier
	v_mov_b32_e32 v1, 0
	v_and_b32_e32 v0, 0x3ff, v2
	v_mul_u32_u24_e32 v0, 0xc08, v0
	v_lshlrev_b32_e32 v0, 2, v0
	v_lshl_add_u64 v[6:7], s[60:61], 0, v[0:1]
	v_add_u32_e32 v0, 0x200, v2
	v_ashrrev_i32_e32 v8, 10, v0
	v_and_b32_e32 v0, 0x3ff, v0
	v_mul_u32_u24_e32 v0, 0xc08, v0
	v_lshlrev_b32_e32 v0, 2, v0
	v_ashrrev_i32_e32 v9, 31, v8
	v_lshl_add_u64 v[10:11], s[60:61], 0, v[0:1]
	v_add_u32_e32 v0, 0x400, v2
	v_lshl_add_u64 v[8:9], v[8:9], 2, v[10:11]
	v_ashrrev_i32_e32 v10, 10, v0
	v_add_u32_e32 v0, 0x600, v2
	v_ashrrev_i32_e32 v12, 10, v0
	v_and_b32_e32 v0, 0x3ff, v0
	v_mul_u32_u24_e32 v0, 0xc08, v0
	v_lshlrev_b32_e32 v0, 2, v0
	v_ashrrev_i32_e32 v13, 31, v12
	v_lshl_add_u64 v[14:15], s[60:61], 0, v[0:1]
	v_add_u32_e32 v0, 0x800, v2
	v_lshl_add_u64 v[12:13], v[12:13], 2, v[14:15]
	v_ashrrev_i32_e32 v14, 10, v0
	v_add_u32_e32 v0, 0xa00, v2
	v_ashrrev_i32_e32 v16, 10, v0
	v_and_b32_e32 v0, 0x3ff, v0
	v_mul_u32_u24_e32 v0, 0xc08, v0
	s_mov_b64 s[0:1], 0x3000
	v_lshlrev_b32_e32 v0, 2, v0
	v_lshl_add_u64 v[6:7], v[6:7], 0, s[0:1]
	s_movk_i32 s0, 0x3000
	v_ashrrev_i32_e32 v17, 31, v16
	v_lshl_add_u64 v[18:19], s[60:61], 0, v[0:1]
	v_add_u32_e32 v0, 0xc00, v2
	v_add_co_u32_e32 v8, vcc, s0, v8
	v_lshl_add_u64 v[16:17], v[16:17], 2, v[18:19]
	v_ashrrev_i32_e32 v18, 10, v0
	v_add_u32_e32 v0, 0xe00, v2
	v_addc_co_u32_e32 v9, vcc, 0, v9, vcc
	v_ashrrev_i32_e32 v20, 10, v0
	v_and_b32_e32 v0, 0x3ff, v0
	v_add_co_u32_e32 v12, vcc, s0, v12
	v_mul_u32_u24_e32 v0, 0xc08, v0
	s_nop 0
	v_addc_co_u32_e32 v13, vcc, 0, v13, vcc
	v_lshlrev_b32_e32 v0, 2, v0
	v_ashrrev_i32_e32 v4, 10, v2
	v_add_co_u32_e32 v16, vcc, s0, v16
	v_ashrrev_i32_e32 v21, 31, v20
	v_lshl_add_u64 v[22:23], s[60:61], 0, v[0:1]
	v_ashrrev_i32_e32 v5, 31, v4
	v_addc_co_u32_e32 v17, vcc, 0, v17, vcc
	v_lshl_add_u64 v[20:21], v[20:21], 2, v[22:23]
	v_lshl_add_u64 v[4:5], v[4:5], 2, v[6:7]
	v_ashrrev_i32_e32 v11, 31, v10
	v_ashrrev_i32_e32 v15, 31, v14
	v_ashrrev_i32_e32 v19, 31, v18
	v_add_co_u32_e32 v20, vcc, s0, v20
	v_add_u32_e32 v0, 0x1000, v2
	s_barrier
	v_lshl_add_u64 v[10:11], v[10:11], 2, v[6:7]
	v_lshl_add_u64 v[14:15], v[14:15], 2, v[6:7]
	v_lshl_add_u64 v[18:19], v[18:19], 2, v[6:7]
	v_addc_co_u32_e32 v21, vcc, 0, v21, vcc
	global_load_dword v3, v[4:5], off
	global_load_dword v22, v[8:9], off
	global_load_dword v23, v[10:11], off
	global_load_dword v24, v[12:13], off
	global_load_dword v25, v[14:15], off
	global_load_dword v26, v[16:17], off
	global_load_dword v27, v[18:19], off
	global_load_dword v28, v[20:21], off
	v_ashrrev_i32_e32 v4, 10, v0
	v_add_u32_e32 v0, 0x1200, v2
	v_ashrrev_i32_e32 v8, 10, v0
	v_and_b32_e32 v0, 0x3ff, v0
	v_mul_u32_u24_e32 v0, 0xc08, v0
	v_lshlrev_b32_e32 v0, 2, v0
	v_ashrrev_i32_e32 v9, 31, v8
	v_lshl_add_u64 v[10:11], s[60:61], 0, v[0:1]
	v_add_u32_e32 v0, 0x1400, v2
	v_lshl_add_u64 v[8:9], v[8:9], 2, v[10:11]
	v_ashrrev_i32_e32 v10, 10, v0
	v_add_u32_e32 v0, 0x1600, v2
	v_ashrrev_i32_e32 v12, 10, v0
	v_and_b32_e32 v0, 0x3ff, v0
	v_mul_u32_u24_e32 v0, 0xc08, v0
	v_lshlrev_b32_e32 v0, 2, v0
	v_ashrrev_i32_e32 v13, 31, v12
	v_lshl_add_u64 v[14:15], s[60:61], 0, v[0:1]
	v_add_u32_e32 v0, 0x1800, v2
	v_lshl_add_u64 v[12:13], v[12:13], 2, v[14:15]
	v_ashrrev_i32_e32 v14, 10, v0
	v_add_u32_e32 v0, 0x1a00, v2
	v_ashrrev_i32_e32 v16, 10, v0
	v_and_b32_e32 v0, 0x3ff, v0
	v_mul_u32_u24_e32 v0, 0xc08, v0
	v_lshlrev_b32_e32 v0, 2, v0
	v_ashrrev_i32_e32 v17, 31, v16
	v_lshl_add_u64 v[18:19], s[60:61], 0, v[0:1]
	v_add_u32_e32 v0, 0x1c00, v2
	v_lshl_add_u64 v[16:17], v[16:17], 2, v[18:19]
	v_ashrrev_i32_e32 v18, 10, v0
	v_ashrrev_i32_e32 v5, 31, v4
	v_add_co_u32_e32 v8, vcc, s0, v8
	v_ashrrev_i32_e32 v11, 31, v10
	v_ashrrev_i32_e32 v15, 31, v14
	v_ashrrev_i32_e32 v19, 31, v18
	v_add_u32_e32 v0, 0x1e00, v2
	v_lshl_add_u64 v[4:5], v[4:5], 2, v[6:7]
	v_addc_co_u32_e32 v9, vcc, 0, v9, vcc
	v_lshl_add_u64 v[10:11], v[10:11], 2, v[6:7]
	v_lshl_add_u64 v[14:15], v[14:15], 2, v[6:7]
	v_lshl_add_u64 v[6:7], v[18:19], 2, v[6:7]
	v_ashrrev_i32_e32 v18, 10, v0
	v_and_b32_e32 v0, 0x3ff, v0
	v_add_co_u32_e32 v12, vcc, s0, v12
	v_mul_u32_u24_e32 v0, 0xc08, v0
	s_nop 0
	v_addc_co_u32_e32 v13, vcc, 0, v13, vcc
	v_lshlrev_b32_e32 v0, 2, v0
	v_add_co_u32_e32 v16, vcc, s0, v16
	v_ashrrev_i32_e32 v19, 31, v18
	v_lshl_add_u64 v[20:21], s[60:61], 0, v[0:1]
	v_addc_co_u32_e32 v17, vcc, 0, v17, vcc
	v_lshl_add_u64 v[18:19], v[18:19], 2, v[20:21]
	v_add_co_u32_e32 v18, vcc, s0, v18
	s_lshl_b32 s0, s94, 3
	s_nop 0
	v_addc_co_u32_e32 v19, vcc, 0, v19, vcc
	global_load_dword v0, v[4:5], off
	s_nop 0
	global_load_dword v4, v[8:9], off
	global_load_dword v5, v[10:11], off
	s_nop 0
	global_load_dword v8, v[12:13], off
	global_load_dword v9, v[14:15], off
	global_load_dword v10, v[16:17], off
	s_nop 0
	global_load_dword v6, v[6:7], off
	s_nop 0
	global_load_dword v7, v[18:19], off
	s_add_u32 s40, s92, 0x1800000
	s_addc_u32 s41, s93, 0
	v_lshl_add_u32 v11, v2, 2, 0
	s_abs_i32 s5, s0
	s_waitcnt vmcnt(14)
	ds_write2st64_b32 v11, v3, v22 offset1:8
	s_waitcnt vmcnt(12)
	ds_write2st64_b32 v11, v23, v24 offset0:16 offset1:24
	s_waitcnt vmcnt(10)
	ds_write2st64_b32 v11, v25, v26 offset0:32 offset1:40
	s_waitcnt vmcnt(8)
	ds_write2st64_b32 v11, v27, v28 offset0:48 offset1:56
	s_waitcnt vmcnt(6)
	ds_write2st64_b32 v11, v0, v4 offset0:64 offset1:72
	s_waitcnt vmcnt(4)
	ds_write2st64_b32 v11, v5, v8 offset0:80 offset1:88
	s_waitcnt vmcnt(2)
	ds_write2st64_b32 v11, v9, v10 offset0:96 offset1:104
	s_waitcnt vmcnt(0)
	ds_write2st64_b32 v11, v6, v7 offset0:112 offset1:120
	v_readfirstlane_b32 s1, v2
	s_nop 3
	s_ashr_i32 s1, s1, 6
	s_mul_i32 s50, s2, 0x81
	s_lshl_b32 s0, s1, 4
	s_add_i32 s50, s50, s0
	s_cmp_lg_u32 s1, 0
	s_cselect_b32 s0, 1, 0
	s_add_i32 s50, s50, s0
	s_add_i32 s3, s50, 16
	s_xor_b32 s0, s0, 1
	s_add_i32 s3, s3, s0
	s_cmp_lt_i32 s50, s3
	v_mbcnt_lo_u32_b32 v202, -1, 0
	s_waitcnt lgkmcnt(0)
	s_barrier
; __global__ void __launch_bounds__(NTHR, 2) hymba_fwd(Params P) {
;     ...
;         int cur_b = -1; f32x4 Ak[4], Bk[4]; float bsel = 0.f;
;         for (int j = 0; j < 4; ++j) { Ak[j] = (f32x4){0.f, 0.f, 0.f, 0.f}; Bk[j] = Ak[j]; }
;         f32x4 x0[4], x1[4];
;         auto rowptr = [&](int m) -> const float* { return (m < PT) ? P.x_prompt + (size_t)m * DM : P.x_sample + (size_t)(m - PT) * DM; };
;         if (p_lo < p_hi) { const float* r0 = rowptr(2 * p_lo); const float* r1 = rowptr(2 * p_lo + 1);
; #pragma unroll
;             for (int j = 0; j < 4; ++j) { x0[j] = __builtin_nontemporal_load((const f32x4*)r0 + lane + 64 * j); x1[j] = __builtin_nontemporal_load((const f32x4*)r1 + lane + 64 * j); } }
	s_cbranch_scc0 .LBB0_150
	s_lshl_b32 s44, s50, 1
	s_add_i32 s0, s44, 0xffff0000
	s_ashr_i32 s1, s44, 31
	s_cmp_lt_i32 s50, 0x8000
	s_cselect_b32 s1, s1, 0
	s_cselect_b32 s0, s44, s0
	s_cselect_b32 s4, s37, s39
	s_cselect_b32 s5, s36, s38
	s_lshl_b64 s[0:1], s[0:1], 12
	s_add_u32 s0, s5, s0
	s_addc_u32 s1, s4, s1
	s_or_b32 s4, s44, 1
	s_add_i32 s6, s44, 0xffff0001
	s_ashr_i32 s5, s4, 31
	s_cmp_lt_i32 s4, 0x10000
	s_cselect_b32 s5, s5, 0
	s_cselect_b32 s4, s4, s6
	v_and_b32_e32 v4, 63, v2
	s_cselect_b32 s6, s37, s39
	s_cselect_b32 s7, s36, s38
	s_lshl_b64 s[4:5], s[4:5], 12
	s_add_u32 s4, s7, s4
	v_lshlrev_b32_e32 v100, 4, v4
	s_addc_u32 s5, s6, s5
	global_load_dwordx4 v[96:99], v100, s[0:1] nt
	global_load_dwordx4 v[88:91], v100, s[0:1] offset:1024 nt
	global_load_dwordx4 v[92:95], v100, s[4:5] nt
	global_load_dwordx4 v[84:87], v100, s[4:5] offset:1024 nt
	global_load_dwordx4 v[48:51], v100, s[0:1] offset:2048 nt
	global_load_dwordx4 v[40:43], v100, s[0:1] offset:3072 nt
	global_load_dwordx4 v[44:47], v100, s[4:5] offset:2048 nt
	global_load_dwordx4 v[36:39], v100, s[4:5] offset:3072 nt
	v_and_b32_e32 v3, 32, v2
	v_cmp_eq_u32_e64 s[0:1], 0, v3
	v_and_b32_e32 v3, 16, v2
	v_cmp_eq_u32_e64 s[4:5], 0, v3
	v_and_b32_e32 v3, 8, v2
	v_cmp_eq_u32_e64 s[6:7], 0, v3
	v_and_b32_e32 v3, 4, v2
	v_lshlrev_b32_e32 v6, 2, v4
	v_bfe_u32 v102, v2, 2, 3
	v_cmp_eq_u32_e64 s[8:9], 0, v3
	v_lshlrev_b32_e32 v8, 3, v4
	v_mov_b32_e32 v9, v1
	v_and_b32_e32 v3, 3, v2
	v_lshlrev_b32_e32 v0, 2, v102
	v_lshl_add_u64 v[106:107], s[40:41], 0, v[8:9]
	v_cmp_eq_u32_e64 s[10:11], 0, v3
	v_bfe_u32 v103, v2, 5, 1
	v_cmp_gt_u32_e64 s[12:13], 32, v4
	v_mov_b32_e32 v101, v1
	v_or_b32_e32 v8, 0x100, v6
	v_or_b32_e32 v10, 0x200, v6
	v_or_b32_e32 v12, 0x300, v6
	v_mov_b32_e32 v2, v1
	v_mov_b32_e32 v3, v1
	v_lshlrev_b32_e32 v130, 4, v4
	v_lshl_add_u64 v[104:105], s[62:63], 0, v[0:1]
	v_lshl_add_u64 v[108:109], s[42:43], 0, v[0:1]
	v_lshl_add_u64 v[110:111], s[58:59], 0, v[100:101]
	v_mov_b32_e32 v0, v1
	v_lshlrev_b32_e32 v101, 2, v6
	v_lshlrev_b32_e32 v113, 2, v8
	v_lshlrev_b32_e32 v128, 2, v10
	v_lshlrev_b32_e32 v129, 2, v12
	v_mov_b64_e32 v[6:7], v[2:3]
	v_mov_b64_e32 v[10:11], v[2:3]
	v_mov_b64_e32 v[14:15], v[2:3]
	v_mov_b64_e32 v[26:27], v[2:3]
	v_mov_b64_e32 v[18:19], v[2:3]
	v_mov_b64_e32 v[22:23], v[2:3]
	v_mov_b64_e32 v[30:31], v[2:3]
	v_mov_b64_e32 v[34:35], v[2:3]
	v_cmp_eq_u32_e64 s[14:15], 1, v102
	v_cmp_eq_u32_e64 s[16:17], 2, v102
	v_cmp_eq_u32_e64 s[18:19], 3, v102
	v_cmp_eq_u32_e64 s[20:21], 4, v102
	v_cmp_eq_u32_e64 s[22:23], 5, v102
	v_cmp_eq_u32_e64 s[24:25], 6, v102
	v_cmp_eq_u32_e64 s[26:27], 7, v102
	s_mov_b32 s51, -1
	v_mbcnt_hi_u32_b32 v131, -1, v202
	s_mov_b32 s33, 0x800000
	v_mov_b32_e32 v132, 0x3ecc95a3
	s_mov_b32 s34, 0xffff
	s_movk_i32 s35, 0x840
	v_mov_b32_e32 v112, 0x358637bd
	v_mov_b32_e32 v133, 0x7f800000
	v_mov_b32_e32 v134, 0x7fc00000
	v_mov_b32_e32 v135, 0xff800000
	v_mov_b64_e32 v[4:5], v[0:1]
	v_mov_b64_e32 v[8:9], v[0:1]
	v_mov_b64_e32 v[12:13], v[0:1]
	v_mov_b64_e32 v[24:25], v[0:1]
	v_mov_b64_e32 v[16:17], v[0:1]
	v_mov_b64_e32 v[20:21], v[0:1]
	v_mov_b64_e32 v[28:29], v[0:1]
	v_mov_b64_e32 v[32:33], v[0:1]
	v_mov_b32_e32 v136, 0
	s_branch .LBB0_143
